# hyena: gv image in LDS padded to 80-byte block stride (conflict-free ds_read_b128 of the B operand)
# speedup vs baseline: 1.0203x; 1.0031x over previous
.Lhy_gr_short:
	s_lshl_b32 s4, s6, 5
	s_and_b32 s4, s4, 0xfffff800
	s_add_i32 s6, s4, 0xfffff800
	s_and_b64 s[4:5], s[40:41], exec
	s_cselect_b32 s44, s6, 0x1000
	v_mad_i64_i32 v[10:11], s[4:5], v2, s68, 0
	s_ashr_i32 s45, s44, 31
	s_add_i32 s4, 0, 0x10000
	v_add_u32_e32 v6, s4, v3
	v_lshrrev_b32_e32 v88, 2, v8
	v_lshlrev_b32_e32 v88, 4, v88
	v_lshl_add_u32 v88, v35, 10, v88
	v_add_u32_e32 v6, v6, v88
	s_lshl_b64 s[4:5], s[44:45], 1
	v_readlane_b32 s10, v254, 47
	v_readlane_b32 s11, v254, 48
	s_add_u32 s4, s10, s4
	v_or_b32_e32 v10, v10, v4
	s_addc_u32 s5, s11, s5
	v_lshl_add_u64 v[2:3], s[4:5], 0, v[10:11]
	global_load_dwordx4 v[72:75], v[2:3], off
	global_load_dwordx4 v[76:79], v[2:3], off offset:1024
	global_load_dwordx4 v[80:83], v[2:3], off offset:2048
	global_load_dwordx4 v[84:87], v[2:3], off offset:3072
	s_waitcnt vmcnt(4)
	ds_write_b128 v9, v[56:59]
	s_and_b64 vcc, exec, s[40:41]
	s_cbranch_vccnz .Lhy_gw_short
	ds_write_b128 v9, v[60:63] offset:1024
	ds_write_b128 v9, v[64:67] offset:2048
	ds_write_b128 v9, v[68:71] offset:3072
.Lhy_gw_short:
	s_waitcnt vmcnt(0)
	ds_write_b128 v6, v[72:75]
	ds_write_b128 v6, v[76:79] offset:1280
	ds_write_b128 v6, v[80:83] offset:2560
	ds_write_b128 v6, v[84:87] offset:3840
	s_or_b64 exec, exec, s[14:15]
	v_cmp_gt_i32_e32 vcc, 8, v34
	s_and_saveexec_b64 s[14:15], vcc
	v_lshl_add_u32 v0, v34, 2, 0
	v_add_u32_e32 v0, 0x1a000, v0
	ds_write_b32 v0, v1
	s_or_b64 exec, exec, s[14:15]
	s_lshr_b32 s6, s7, 5
	s_and_b64 s[4:5], s[40:41], exec
	s_cselect_b32 s10, 3, 5
	s_add_i32 s11, s6, -1
	v_and_b32_e32 v2, 31, v34
	s_and_b64 s[4:5], s[40:41], exec
	s_cselect_b32 s4, 8, 10
	v_lshrrev_b32_e32 v0, s10, v2
	v_lshlrev_b32_e32 v38, s4, v0
	v_or_b32_e32 v0, 32, v2
	v_lshl_add_u32 v3, s7, 2, v5
	v_lshlrev_b32_e32 v2, 1, v2
	v_bitop3_b32 v37, v34, s11, 31 bitop3:0x80
	v_lshrrev_b32_e32 v0, s10, v0
	v_sub_u32_e32 v2, v3, v2
	v_readlane_b32 s5, v253, 18
	v_lshlrev_b32_e32 v0, s4, v0
	v_lshlrev_b32_e32 v4, 1, v0
	v_add_u32_e32 v40, s5, v2
	v_add_u32_e32 v2, s6, v37
	v_lshl_add_u32 v3, v2, 6, v5
	v_lshrrev_b32_e32 v36, 5, v8
	s_lshr_b32 s4, s7, 4
	v_add3_u32 v41, v3, v4, 0
	v_lshlrev_b32_e32 v4, 1, v38
	v_mov_b32_e32 v18, 0
	v_lshlrev_b32_e32 v39, 4, v36
	s_add_i32 s7, s4, -1
	v_add3_u32 v42, v3, v4, 0
	v_lshrrev_b32_e32 v44, 5, v0
	v_lshrrev_b32_e32 v45, 5, v38
	v_add_u32_e32 v44, v44, v2
	v_add_u32_e32 v45, v45, v2
	v_lshlrev_b32_e32 v44, 4, v44
	v_lshlrev_b32_e32 v45, 4, v45
	v_lshl_add_u32 v44, v35, 10, v44
	v_lshl_add_u32 v45, v35, 10, v45
	v_add_u32_e32 v41, v41, v44
	v_add_u32_e32 v42, v42, v45
	v_add_u32_e32 v43, -1, v2
	v_mov_b32_e32 v19, v18
	v_mov_b32_e32 v20, v18
	v_mov_b32_e32 v21, v18
	v_mov_b32_e32 v22, v18
	v_mov_b32_e32 v23, v18
	v_mov_b32_e32 v24, v18
	v_mov_b32_e32 v25, v18
	v_mov_b32_e32 v26, v18
	v_mov_b32_e32 v27, v18
	v_mov_b32_e32 v28, v18
	v_mov_b32_e32 v29, v18
	v_mov_b32_e32 v30, v18
	v_mov_b32_e32 v31, v18
	v_mov_b32_e32 v32, v18
	v_mov_b32_e32 v33, v18
	v_mov_b32_e32 v2, v18
	v_mov_b32_e32 v3, v18
	v_mov_b32_e32 v4, v18
	v_mov_b32_e32 v5, v18
	v_mov_b32_e32 v6, v18
	v_mov_b32_e32 v7, v18
	v_mov_b32_e32 v8, v18
	v_mov_b32_e32 v9, v18
	v_mov_b32_e32 v10, v18
	v_mov_b32_e32 v11, v18
	v_mov_b32_e32 v12, v18
	v_mov_b32_e32 v13, v18
	v_mov_b32_e32 v14, v18
	v_mov_b32_e32 v15, v18
	v_mov_b32_e32 v16, v18
	v_mov_b32_e32 v17, v18
	s_waitcnt lgkmcnt(0)
	s_barrier
	s_add_i32 s4, 0, 0x1a000
	v_mov_b32_e32 v54, s4
	v_add_u32_e32 v52, v40, v39
	ds_read_u16 v104, v52
	ds_read_u16 v105, v52 offset:2
	ds_read_u16 v106, v52 offset:4
	ds_read_u16 v107, v52 offset:6
	ds_read_u16 v108, v52 offset:8
	ds_read_u16 v109, v52 offset:10
	ds_read_u16 v110, v52 offset:12
	ds_read_u16 v111, v52 offset:14
	v_cmp_lt_i32_e32 vcc, -1, v43
	v_cmp_gt_i32_e64 s[40:41], s6, v43
	v_add_u32_e32 v53, v42, v39
	v_add_u32_e32 v55, v41, v39
	s_and_b64 vcc, vcc, s[40:41]
	v_add_u32_e32 v120, 0xffb0, v53
	v_add_u32_e32 v121, 0xffb0, v55
	v_add_u32_e32 v122, 0xffd0, v53
	v_add_u32_e32 v123, 0xffd0, v55
	v_cndmask_b32_e32 v120, v54, v120, vcc
	v_cndmask_b32_e32 v121, v54, v121, vcc
	v_cndmask_b32_e32 v122, v54, v122, vcc
	v_cndmask_b32_e32 v123, v54, v123, vcc
	ds_read_b128 v[48:51], v120
	ds_read_b128 v[92:95], v121
	ds_read_b128 v[96:99], v122
	ds_read_b128 v[100:103], v123
	s_waitcnt lgkmcnt(7)
	ds_read_u16 v112, v52 offset:32
	ds_read_u16 v113, v52 offset:34
	ds_read_u16 v114, v52 offset:36
	ds_read_u16 v115, v52 offset:38
	ds_read_u16 v116, v52 offset:40
	ds_read_u16 v117, v52 offset:42
	ds_read_u16 v118, v52 offset:44
	ds_read_u16 v119, v52 offset:46
	v_subrev_u32_e32 v40, 64, v40
	v_subrev_u32_e32 v41, 0x50, v41
	v_subrev_u32_e32 v42, 0x50, v42
	v_add_u32_e32 v43, -1, v43
	s_waitcnt lgkmcnt(0)
	v_perm_b32 v44, v105, v104, s86
	v_perm_b32 v45, v107, v106, s86
	v_perm_b32 v46, v109, v108, s86
	v_perm_b32 v47, v111, v110, s86
	v_perm_b32 v88, v113, v112, s86
	v_perm_b32 v89, v115, v114, s86
	v_perm_b32 v90, v117, v116, s86
	v_perm_b32 v91, v119, v118, s86
.LBB0_532:
	v_mfma_f32_32x32x16_bf16 v[18:33], v[44:47], v[48:51], v[18:33]
	v_mfma_f32_32x32x16_bf16 v[2:17], v[44:47], v[92:95], v[2:17]
	v_mfma_f32_32x32x16_bf16 v[18:33], v[88:91], v[96:99], v[18:33]
	v_mfma_f32_32x32x16_bf16 v[2:17], v[88:91], v[100:103], v[2:17]
	s_add_i32 s7, s7, -1
	v_add_u32_e32 v52, v40, v39
	ds_read_u16 v104, v52
	ds_read_u16 v105, v52 offset:2
	ds_read_u16 v106, v52 offset:4
	ds_read_u16 v107, v52 offset:6
	ds_read_u16 v108, v52 offset:8
	ds_read_u16 v109, v52 offset:10
	ds_read_u16 v110, v52 offset:12
	ds_read_u16 v111, v52 offset:14
	v_cmp_lt_i32_e32 vcc, -1, v43
	v_cmp_gt_i32_e64 s[40:41], s6, v43
	v_add_u32_e32 v53, v42, v39
	v_add_u32_e32 v55, v41, v39
	s_and_b64 vcc, vcc, s[40:41]
	v_add_u32_e32 v120, 0xffb0, v53
	v_add_u32_e32 v121, 0xffb0, v55
	v_add_u32_e32 v122, 0xffd0, v53
	v_add_u32_e32 v123, 0xffd0, v55
	v_cndmask_b32_e32 v120, v54, v120, vcc
	v_cndmask_b32_e32 v121, v54, v121, vcc
	v_cndmask_b32_e32 v122, v54, v122, vcc
	v_cndmask_b32_e32 v123, v54, v123, vcc
	ds_read_b128 v[48:51], v120
	ds_read_b128 v[92:95], v121
	ds_read_b128 v[96:99], v122
	ds_read_b128 v[100:103], v123
	s_waitcnt lgkmcnt(7)
	ds_read_u16 v112, v52 offset:32
	ds_read_u16 v113, v52 offset:34
	ds_read_u16 v114, v52 offset:36
	ds_read_u16 v115, v52 offset:38
	ds_read_u16 v116, v52 offset:40
	ds_read_u16 v117, v52 offset:42
	ds_read_u16 v118, v52 offset:44
	ds_read_u16 v119, v52 offset:46
	v_subrev_u32_e32 v40, 64, v40
	v_subrev_u32_e32 v41, 0x50, v41
	v_subrev_u32_e32 v42, 0x50, v42
	v_add_u32_e32 v43, -1, v43
	s_waitcnt lgkmcnt(0)
	v_perm_b32 v44, v105, v104, s86
	v_perm_b32 v45, v107, v106, s86
	v_perm_b32 v46, v109, v108, s86
	v_perm_b32 v47, v111, v110, s86
	v_perm_b32 v88, v113, v112, s86
	v_perm_b32 v89, v115, v114, s86
	v_perm_b32 v90, v117, v116, s86
	v_perm_b32 v91, v119, v118, s86
	s_cmp_lg_u32 s7, 0
	s_cbranch_scc1 .LBB0_532
	s_barrier
	v_lshlrev_b32_e32 v37, 5, v37
	v_lshlrev_b32_e32 v36, 2, v36
	v_add_u32_e32 v38, v38, v37
	v_lshl_add_u32 v35, v35, 1, 0
	v_or_b32_e32 v38, v38, v36
	v_bfe_u32 v39, v18, 16, 1
	v_add3_u32 v18, v18, v39, s27
	v_lshrrev_b32_e32 v56, 5, v38
	v_lshl_add_u32 v38, v38, 4, v35
	v_lshl_add_u32 v38, v56, 4, v38
	ds_write_b16_d16_hi v38, v18
	v_bfe_u32 v18, v19, 16, 1
	v_add3_u32 v18, v19, v18, s27
	ds_write_b16_d16_hi v38, v18 offset:16
	v_bfe_u32 v18, v20, 16, 1
	v_add3_u32 v18, v20, v18, s27
	ds_write_b16_d16_hi v38, v18 offset:32
	v_bfe_u32 v18, v21, 16, 1
	v_add3_u32 v18, v21, v18, s27
	ds_write_b16_d16_hi v38, v18 offset:48
	v_bfe_u32 v18, v22, 16, 1
	v_add3_u32 v18, v22, v18, s27
	ds_write_b16_d16_hi v38, v18 offset:128
	v_bfe_u32 v18, v23, 16, 1
	v_add3_u32 v18, v23, v18, s27
	ds_write_b16_d16_hi v38, v18 offset:144
	v_bfe_u32 v18, v24, 16, 1
	v_add3_u32 v18, v24, v18, s27
	ds_write_b16_d16_hi v38, v18 offset:160
	v_bfe_u32 v18, v25, 16, 1
	v_add3_u32 v18, v25, v18, s27
	ds_write_b16_d16_hi v38, v18 offset:176
	v_bfe_u32 v18, v26, 16, 1
	v_add3_u32 v18, v26, v18, s27
	ds_write_b16_d16_hi v38, v18 offset:256
	v_bfe_u32 v18, v27, 16, 1
	v_add3_u32 v18, v27, v18, s27
	ds_write_b16_d16_hi v38, v18 offset:272
	v_bfe_u32 v18, v28, 16, 1
	v_add3_u32 v18, v28, v18, s27
	ds_write_b16_d16_hi v38, v18 offset:288
	v_bfe_u32 v18, v29, 16, 1
	v_add3_u32 v18, v29, v18, s27
	ds_write_b16_d16_hi v38, v18 offset:304
	v_bfe_u32 v18, v30, 16, 1
	v_add3_u32 v18, v30, v18, s27
	ds_write_b16_d16_hi v38, v18 offset:384
	v_bfe_u32 v18, v31, 16, 1
	v_add3_u32 v18, v31, v18, s27
	ds_write_b16_d16_hi v38, v18 offset:400
	v_bfe_u32 v18, v32, 16, 1
	v_add3_u32 v18, v32, v18, s27
	ds_write_b16_d16_hi v38, v18 offset:416
	v_bfe_u32 v18, v33, 16, 1
	v_add3_u32 v18, v33, v18, s27
	v_add_u32_e32 v0, v0, v37
	ds_write_b16_d16_hi v38, v18 offset:432
	v_or_b32_e32 v0, v0, v36
	v_bfe_u32 v18, v2, 16, 1
	v_add3_u32 v2, v2, v18, s27
	v_lshrrev_b32_e32 v57, 5, v0
	v_lshl_add_u32 v0, v0, 4, v35
	v_lshl_add_u32 v0, v57, 4, v0
	ds_write_b16_d16_hi v0, v2
	v_bfe_u32 v2, v3, 16, 1
	v_add3_u32 v2, v3, v2, s27
	ds_write_b16_d16_hi v0, v2 offset:16
	v_bfe_u32 v2, v4, 16, 1
	v_add3_u32 v2, v4, v2, s27
	ds_write_b16_d16_hi v0, v2 offset:32
	v_bfe_u32 v2, v5, 16, 1
	v_add3_u32 v2, v5, v2, s27
	ds_write_b16_d16_hi v0, v2 offset:48
	v_bfe_u32 v2, v6, 16, 1
	v_add3_u32 v2, v6, v2, s27
	ds_write_b16_d16_hi v0, v2 offset:128
	v_bfe_u32 v2, v7, 16, 1
	v_add3_u32 v2, v7, v2, s27
	ds_write_b16_d16_hi v0, v2 offset:144
	v_bfe_u32 v2, v8, 16, 1
	v_add3_u32 v2, v8, v2, s27
	ds_write_b16_d16_hi v0, v2 offset:160
	v_bfe_u32 v2, v9, 16, 1
	v_add3_u32 v2, v9, v2, s27
	ds_write_b16_d16_hi v0, v2 offset:176
	v_bfe_u32 v2, v10, 16, 1
	v_add3_u32 v2, v10, v2, s27
	ds_write_b16_d16_hi v0, v2 offset:256
	v_bfe_u32 v2, v11, 16, 1
	v_add3_u32 v2, v11, v2, s27
	ds_write_b16_d16_hi v0, v2 offset:272
	v_bfe_u32 v2, v12, 16, 1
	v_add3_u32 v2, v12, v2, s27
	ds_write_b16_d16_hi v0, v2 offset:288
	v_bfe_u32 v2, v13, 16, 1
	v_add3_u32 v2, v13, v2, s27
	ds_write_b16_d16_hi v0, v2 offset:304
	v_bfe_u32 v2, v14, 16, 1
	v_add3_u32 v2, v14, v2, s27
	ds_write_b16_d16_hi v0, v2 offset:384
	v_bfe_u32 v2, v15, 16, 1
	v_add3_u32 v2, v15, v2, s27
	ds_write_b16_d16_hi v0, v2 offset:400
	v_bfe_u32 v2, v16, 16, 1
	v_add3_u32 v2, v16, v2, s27
	ds_write_b16_d16_hi v0, v2 offset:416
	v_bfe_u32 v2, v17, 16, 1
	s_movk_i32 s4, 0x800
	v_add3_u32 v2, v17, v2, s27
	v_cmp_gt_i32_e32 vcc, s4, v34
	ds_write_b16_d16_hi v0, v2 offset:432
	s_waitcnt lgkmcnt(0)
	s_barrier
	s_and_saveexec_b64 s[40:41], vcc
	s_mov_b64 s[10:11], 0x100000
	s_cbranch_execz .LBB0_497
	s_add_i32 s4, s38, s3
	s_ashr_i32 s5, s4, 31
	s_lshl_b64 s[4:5], s[4:5], 2
	s_add_u32 s4, s42, s4
	s_addc_u32 s5, s43, s5
	global_load_dwordx4 v[2:5], v1, s[4:5] offset:16
	global_load_dwordx4 v[6:9], v1, s[4:5]
	s_ashr_i32 s39, s38, 31
	v_add_u32_e32 v12, s44, v34
	s_lshl_b64 s[4:5], s[38:39], 1
	v_readlane_b32 s6, v253, 50
	v_ashrrev_i32_e32 v13, 31, v12
	v_readlane_b32 s7, v253, 51
	s_add_u32 s6, s6, s4
	v_lshlrev_b64 v[10:11], 11, v[12:13]
	s_addc_u32 s7, s7, s5
	v_lshl_add_u64 v[10:11], s[6:7], 0, v[10:11]
	v_readlane_b32 s6, v254, 49
	v_readlane_b32 s7, v254, 50
	s_add_u32 s4, s6, s4
	v_lshlrev_b64 v[12:13], 10, v[12:13]
	s_addc_u32 s5, s7, s5
	v_add_u32_e32 v0, 0xfffffe00, v34
	v_lshl_add_u32 v14, v34, 4, 0
	v_lshrrev_b32_e32 v15, 5, v34
	v_lshl_add_u32 v14, v15, 4, v14
	v_lshl_add_u64 v[12:13], s[4:5], 0, v[12:13]
	s_mov_b64 s[38:39], 0
	s_mov_b64 s[4:5], 0x80000
	global_load_dwordx4 v[56:59], v[12:13], off
	v_add_co_u32_e32 v24, vcc, 0x600000, v12
	s_nop 1
	v_addc_co_u32_e32 v25, vcc, 0, v13, vcc
	global_load_dwordx4 v[72:75], v[24:25], off
	ds_read_b128 v[88:91], v14
	v_lshl_add_u64 v[12:13], v[12:13], 0, s[4:5]
	global_load_dwordx4 v[60:63], v[12:13], off
	v_add_co_u32_e32 v24, vcc, 0x600000, v12
	s_nop 1
	v_addc_co_u32_e32 v25, vcc, 0, v13, vcc
	global_load_dwordx4 v[76:79], v[24:25], off
	ds_read_b128 v[92:95], v14 offset:8448
	v_lshl_add_u64 v[12:13], v[12:13], 0, s[4:5]
	global_load_dwordx4 v[64:67], v[12:13], off
	v_add_co_u32_e32 v24, vcc, 0x600000, v12
	s_nop 1
	v_addc_co_u32_e32 v25, vcc, 0, v13, vcc
	global_load_dwordx4 v[80:83], v[24:25], off
	ds_read_b128 v[96:99], v14 offset:16896
	v_lshl_add_u64 v[12:13], v[12:13], 0, s[4:5]
	global_load_dwordx4 v[68:71], v[12:13], off
	v_add_co_u32_e32 v24, vcc, 0x600000, v12
	s_nop 1
	v_addc_co_u32_e32 v25, vcc, 0, v13, vcc
	global_load_dwordx4 v[84:87], v[24:25], off
	ds_read_b128 v[100:103], v14 offset:25344
	v_lshl_add_u64 v[12:13], v[12:13], 0, s[4:5]
	s_waitcnt vmcnt(6) lgkmcnt(3)
	v_mov_b32_e32 v16, v88
	v_mov_b32_e32 v17, v89
	v_mov_b32_e32 v18, v90
	v_mov_b32_e32 v19, v91
	v_mov_b32_e32 v20, v56
	v_mov_b32_e32 v21, v57
	v_mov_b32_e32 v22, v58
	v_mov_b32_e32 v23, v59
	v_mov_b32_e32 v24, v72
	v_mov_b32_e32 v25, v73
	v_mov_b32_e32 v26, v74
	v_mov_b32_e32 v27, v75
	v_and_b32_e32 v31, 0xffff0000, v16
	v_lshlrev_b32_e32 v30, 16, v16
	v_and_b32_e32 v29, 0xffff0000, v20
	v_lshlrev_b32_e32 v28, 16, v20
	v_lshlrev_b32_e32 v20, 16, v17
	v_and_b32_e32 v33, 0xffff0000, v24
	v_lshlrev_b32_e32 v32, 16, v24
	v_pk_fma_f32 v[30:31], v[6:7], v[32:33], v[30:31]
	v_lshlrev_b32_e32 v16, 16, v25
	v_pk_mul_f32 v[28:29], v[30:31], v[28:29]
	v_and_b32_e32 v31, 0xffff0000, v21
	v_lshlrev_b32_e32 v30, 16, v21
	v_and_b32_e32 v21, 0xffff0000, v17
	v_and_b32_e32 v17, 0xffff0000, v25
	v_pk_fma_f32 v[16:17], v[8:9], v[16:17], v[20:21]
	v_and_b32_e32 v25, 0xffff0000, v18
	v_pk_mul_f32 v[20:21], v[16:17], v[30:31]
	v_lshlrev_b32_e32 v24, 16, v18
	v_and_b32_e32 v31, 0xffff0000, v26
	v_lshlrev_b32_e32 v30, 16, v26
	v_and_b32_e32 v17, 0xffff0000, v22
	v_lshlrev_b32_e32 v16, 16, v22
	v_pk_fma_f32 v[24:25], v[2:3], v[30:31], v[24:25]
	v_lshlrev_b32_e32 v22, 16, v19
	v_pk_mul_f32 v[24:25], v[24:25], v[16:17]
	v_and_b32_e32 v17, 0xffff0000, v23
	v_lshlrev_b32_e32 v16, 16, v23
	v_and_b32_e32 v23, 0xffff0000, v19
	v_and_b32_e32 v19, 0xffff0000, v27
	v_lshlrev_b32_e32 v18, 16, v27
	v_pk_fma_f32 v[18:19], v[4:5], v[18:19], v[22:23]
	s_nop 0
	v_pk_mul_f32 v[22:23], v[18:19], v[16:17]
	v_cvt_pk_bf16_f32 v16, v28, v29
	v_cvt_pk_bf16_f32 v17, v20, v21
	v_cvt_pk_bf16_f32 v18, v24, v25
	v_cvt_pk_bf16_f32 v19, v22, v23
	global_store_dwordx4 v[10:11], v[16:19], off
	v_lshl_add_u64 v[10:11], v[10:11], 0, s[10:11]
	s_nop 1
	s_waitcnt vmcnt(5) lgkmcnt(2)
	v_mov_b32_e32 v16, v92
	v_mov_b32_e32 v17, v93
	v_mov_b32_e32 v18, v94
	v_mov_b32_e32 v19, v95
	v_mov_b32_e32 v20, v60
	v_mov_b32_e32 v21, v61
	v_mov_b32_e32 v22, v62
	v_mov_b32_e32 v23, v63
	v_mov_b32_e32 v24, v76
	v_mov_b32_e32 v25, v77
	v_mov_b32_e32 v26, v78
	v_mov_b32_e32 v27, v79
	v_and_b32_e32 v31, 0xffff0000, v16
	v_lshlrev_b32_e32 v30, 16, v16
	v_and_b32_e32 v29, 0xffff0000, v20
	v_lshlrev_b32_e32 v28, 16, v20
	v_lshlrev_b32_e32 v20, 16, v17
	v_and_b32_e32 v33, 0xffff0000, v24
	v_lshlrev_b32_e32 v32, 16, v24
	v_pk_fma_f32 v[30:31], v[6:7], v[32:33], v[30:31]
	v_lshlrev_b32_e32 v16, 16, v25
	v_pk_mul_f32 v[28:29], v[30:31], v[28:29]
	v_and_b32_e32 v31, 0xffff0000, v21
	v_lshlrev_b32_e32 v30, 16, v21
	v_and_b32_e32 v21, 0xffff0000, v17
	v_and_b32_e32 v17, 0xffff0000, v25
	v_pk_fma_f32 v[16:17], v[8:9], v[16:17], v[20:21]
	v_and_b32_e32 v25, 0xffff0000, v18
	v_pk_mul_f32 v[20:21], v[16:17], v[30:31]
	v_lshlrev_b32_e32 v24, 16, v18
	v_and_b32_e32 v31, 0xffff0000, v26
	v_lshlrev_b32_e32 v30, 16, v26
	v_and_b32_e32 v17, 0xffff0000, v22
	v_lshlrev_b32_e32 v16, 16, v22
	v_pk_fma_f32 v[24:25], v[2:3], v[30:31], v[24:25]
	v_lshlrev_b32_e32 v22, 16, v19
	v_pk_mul_f32 v[24:25], v[24:25], v[16:17]
	v_and_b32_e32 v17, 0xffff0000, v23
	v_lshlrev_b32_e32 v16, 16, v23
	v_and_b32_e32 v23, 0xffff0000, v19
	v_and_b32_e32 v19, 0xffff0000, v27
	v_lshlrev_b32_e32 v18, 16, v27
	v_pk_fma_f32 v[18:19], v[4:5], v[18:19], v[22:23]
	s_nop 0
	v_pk_mul_f32 v[22:23], v[18:19], v[16:17]
	v_cvt_pk_bf16_f32 v16, v28, v29
	v_cvt_pk_bf16_f32 v17, v20, v21
	v_cvt_pk_bf16_f32 v18, v24, v25
	v_cvt_pk_bf16_f32 v19, v22, v23
	global_store_dwordx4 v[10:11], v[16:19], off
	v_lshl_add_u64 v[10:11], v[10:11], 0, s[10:11]
	s_nop 1
	s_waitcnt vmcnt(4) lgkmcnt(1)
	v_mov_b32_e32 v16, v96
	v_mov_b32_e32 v17, v97
	v_mov_b32_e32 v18, v98
	v_mov_b32_e32 v19, v99
	v_mov_b32_e32 v20, v64
	v_mov_b32_e32 v21, v65
	v_mov_b32_e32 v22, v66
	v_mov_b32_e32 v23, v67
	v_mov_b32_e32 v24, v80
	v_mov_b32_e32 v25, v81
	v_mov_b32_e32 v26, v82
	v_mov_b32_e32 v27, v83
	v_and_b32_e32 v31, 0xffff0000, v16
	v_lshlrev_b32_e32 v30, 16, v16
	v_and_b32_e32 v29, 0xffff0000, v20
	v_lshlrev_b32_e32 v28, 16, v20
	v_lshlrev_b32_e32 v20, 16, v17
	v_and_b32_e32 v33, 0xffff0000, v24
	v_lshlrev_b32_e32 v32, 16, v24
	v_pk_fma_f32 v[30:31], v[6:7], v[32:33], v[30:31]
	v_lshlrev_b32_e32 v16, 16, v25
	v_pk_mul_f32 v[28:29], v[30:31], v[28:29]
	v_and_b32_e32 v31, 0xffff0000, v21
	v_lshlrev_b32_e32 v30, 16, v21
	v_and_b32_e32 v21, 0xffff0000, v17
	v_and_b32_e32 v17, 0xffff0000, v25
	v_pk_fma_f32 v[16:17], v[8:9], v[16:17], v[20:21]
	v_and_b32_e32 v25, 0xffff0000, v18
	v_pk_mul_f32 v[20:21], v[16:17], v[30:31]
	v_lshlrev_b32_e32 v24, 16, v18
	v_and_b32_e32 v31, 0xffff0000, v26
	v_lshlrev_b32_e32 v30, 16, v26
	v_and_b32_e32 v17, 0xffff0000, v22
	v_lshlrev_b32_e32 v16, 16, v22
	v_pk_fma_f32 v[24:25], v[2:3], v[30:31], v[24:25]
	v_lshlrev_b32_e32 v22, 16, v19
	v_pk_mul_f32 v[24:25], v[24:25], v[16:17]
	v_and_b32_e32 v17, 0xffff0000, v23
	v_lshlrev_b32_e32 v16, 16, v23
	v_and_b32_e32 v23, 0xffff0000, v19
	v_and_b32_e32 v19, 0xffff0000, v27
	v_lshlrev_b32_e32 v18, 16, v27
	v_pk_fma_f32 v[18:19], v[4:5], v[18:19], v[22:23]
	s_nop 0
	v_pk_mul_f32 v[22:23], v[18:19], v[16:17]
	v_cvt_pk_bf16_f32 v16, v28, v29
	v_cvt_pk_bf16_f32 v17, v20, v21
	v_cvt_pk_bf16_f32 v18, v24, v25
	v_cvt_pk_bf16_f32 v19, v22, v23
	global_store_dwordx4 v[10:11], v[16:19], off
	v_lshl_add_u64 v[10:11], v[10:11], 0, s[10:11]
	s_nop 1
	s_waitcnt vmcnt(3) lgkmcnt(0)
	v_mov_b32_e32 v16, v100
	v_mov_b32_e32 v17, v101
	v_mov_b32_e32 v18, v102
	v_mov_b32_e32 v19, v103
	v_mov_b32_e32 v20, v68
	v_mov_b32_e32 v21, v69
	v_mov_b32_e32 v22, v70
	v_mov_b32_e32 v23, v71
	v_mov_b32_e32 v24, v84
	v_mov_b32_e32 v25, v85
	v_mov_b32_e32 v26, v86
	v_mov_b32_e32 v27, v87
	v_and_b32_e32 v31, 0xffff0000, v16
	v_lshlrev_b32_e32 v30, 16, v16
	v_and_b32_e32 v29, 0xffff0000, v20
	v_lshlrev_b32_e32 v28, 16, v20
	v_lshlrev_b32_e32 v20, 16, v17
	v_and_b32_e32 v33, 0xffff0000, v24
	v_lshlrev_b32_e32 v32, 16, v24
	v_pk_fma_f32 v[30:31], v[6:7], v[32:33], v[30:31]
	v_lshlrev_b32_e32 v16, 16, v25
	v_pk_mul_f32 v[28:29], v[30:31], v[28:29]
	v_and_b32_e32 v31, 0xffff0000, v21
	v_lshlrev_b32_e32 v30, 16, v21
	v_and_b32_e32 v21, 0xffff0000, v17
	v_and_b32_e32 v17, 0xffff0000, v25
	v_pk_fma_f32 v[16:17], v[8:9], v[16:17], v[20:21]
	v_and_b32_e32 v25, 0xffff0000, v18
	v_pk_mul_f32 v[20:21], v[16:17], v[30:31]
	v_lshlrev_b32_e32 v24, 16, v18
	v_and_b32_e32 v31, 0xffff0000, v26
	v_lshlrev_b32_e32 v30, 16, v26
	v_and_b32_e32 v17, 0xffff0000, v22
	v_lshlrev_b32_e32 v16, 16, v22
	v_pk_fma_f32 v[24:25], v[2:3], v[30:31], v[24:25]
	v_lshlrev_b32_e32 v22, 16, v19
	v_pk_mul_f32 v[24:25], v[24:25], v[16:17]
	v_and_b32_e32 v17, 0xffff0000, v23
	v_lshlrev_b32_e32 v16, 16, v23
	v_and_b32_e32 v23, 0xffff0000, v19
	v_and_b32_e32 v19, 0xffff0000, v27
	v_lshlrev_b32_e32 v18, 16, v27
	v_pk_fma_f32 v[18:19], v[4:5], v[18:19], v[22:23]
	s_nop 0
	v_pk_mul_f32 v[22:23], v[18:19], v[16:17]
	v_cvt_pk_bf16_f32 v16, v28, v29
	v_cvt_pk_bf16_f32 v17, v20, v21
	v_cvt_pk_bf16_f32 v18, v24, v25
	v_cvt_pk_bf16_f32 v19, v22, v23
	global_store_dwordx4 v[10:11], v[16:19], off
	v_lshl_add_u64 v[10:11], v[10:11], 0, s[10:11]
	s_nop 1
	s_branch .LBB0_497
